# speedup vs baseline: 1.0077x; 1.0077x over previous
; template <bool ATRANS = false, bool SWAP = true>
; DEV void gemm_seg(f32x4 (&acc)[4][4], bf16_t* As, bf16_t* Bs, const bf16_t* A, const bf16_t* B, int lda, int ldb,
;                   int K, int arow_lo, int arow_hi) {
;     ...
;   GLOAD(0, 0);
;   GLOAD(1, 1);
;   STAB(0, 0);
;   GLOAD(0, 2);
;   for (int kt = 0; kt < nk; kt += 2) {
;     COMPUTE(kt);
;     STAB(1, kt + 1);
;     GLOAD(1, kt + 3);
;     if (kt + 1 >= nk) break;
;     COMPUTE(kt + 1);
;     STAB(0, kt + 2);
;     GLOAD(0, kt + 4);
.Lvm_win1_ok:
	s_setprio 1
	ds_read_b128 v[208:211], v137
	ds_read_b128 v[212:215], v139 offset:36864
	ds_read_b128 v[220:223], v139 offset:38912
	ds_read_b128 v[224:227], v139 offset:40960
	ds_read_b128 v[228:231], v139 offset:43008
	ds_read_b128 v[232:235], v137 offset:2048
	ds_read_b128 v[236:239], v137 offset:4096
	ds_read_b128 v[240:243], v137 offset:6144
	s_waitcnt lgkmcnt(6)
	v_mfma_f32_16x16x32_bf16 v[124:127], v[212:215], v[208:211], v[124:127]
	ds_read_b128 v[244:247], v145
	ds_read_b128 v[248:251], v207 offset:36864
	s_waitcnt lgkmcnt(7)
	v_mfma_f32_16x16x32_bf16 v[120:123], v[220:223], v[208:211], v[120:123]
	s_waitcnt lgkmcnt(6)
	v_mfma_f32_16x16x32_bf16 v[116:119], v[224:227], v[208:211], v[116:119]
	s_waitcnt lgkmcnt(5)
	v_mfma_f32_16x16x32_bf16 v[112:115], v[228:231], v[208:211], v[112:115]
	ds_read_b128 v[208:211], v207 offset:38912
	s_waitcnt lgkmcnt(5)
	v_mfma_f32_16x16x32_bf16 v[108:111], v[212:215], v[232:235], v[108:111]
	v_mfma_f32_16x16x32_bf16 v[104:107], v[220:223], v[232:235], v[104:107]
	v_mfma_f32_16x16x32_bf16 v[100:103], v[224:227], v[232:235], v[100:103]
	v_mfma_f32_16x16x32_bf16 v[96:99], v[228:231], v[232:235], v[96:99]
	ds_read_b128 v[232:235], v207 offset:40960
	s_waitcnt lgkmcnt(5)
	v_mfma_f32_16x16x32_bf16 v[92:95], v[212:215], v[236:239], v[92:95]
	v_mfma_f32_16x16x32_bf16 v[88:91], v[220:223], v[236:239], v[88:91]
	v_mfma_f32_16x16x32_bf16 v[84:87], v[224:227], v[236:239], v[84:87]
	v_mfma_f32_16x16x32_bf16 v[80:83], v[228:231], v[236:239], v[80:83]
	ds_read_b128 v[236:239], v207 offset:43008
	s_waitcnt lgkmcnt(5)
	v_mfma_f32_16x16x32_bf16 v[76:79], v[212:215], v[240:243], v[76:79]
	ds_read_b128 v[212:215], v145 offset:2048
	v_mfma_f32_16x16x32_bf16 v[72:75], v[220:223], v[240:243], v[72:75]
	ds_read_b128 v[220:223], v145 offset:4096
	v_mfma_f32_16x16x32_bf16 v[68:71], v[224:227], v[240:243], v[68:71]
	ds_read_b128 v[224:227], v145 offset:6144
	v_mfma_f32_16x16x32_bf16 v[64:67], v[228:231], v[240:243], v[64:67]
	s_waitcnt vmcnt(8)
	v_cndmask_b32_e64 v0, 0, v0, s[2:3]
	v_cndmask_b32_e64 v1, 0, v1, s[2:3]
	v_cndmask_b32_e64 v2, 0, v2, s[2:3]
	v_cndmask_b32_e64 v3, 0, v3, s[2:3]
	ds_write_b128 v133, v[0:3] offset:18432
	s_waitcnt lgkmcnt(7)
	v_mfma_f32_16x16x32_bf16 v[124:127], v[248:251], v[244:247], v[124:127]
	s_waitcnt lgkmcnt(6)
	v_mfma_f32_16x16x32_bf16 v[120:123], v[208:211], v[244:247], v[120:123]
	v_cndmask_b32_e64 v4, 0, v4, s[4:5]
	v_cndmask_b32_e64 v5, 0, v5, s[4:5]
	v_cndmask_b32_e64 v6, 0, v6, s[4:5]
	v_cndmask_b32_e64 v7, 0, v7, s[4:5]
	ds_write_b128 v133, v[4:7] offset:22528
	s_waitcnt lgkmcnt(6)
	v_mfma_f32_16x16x32_bf16 v[116:119], v[232:235], v[244:247], v[116:119]
	s_waitcnt lgkmcnt(5)
	v_mfma_f32_16x16x32_bf16 v[112:115], v[236:239], v[244:247], v[112:115]
	v_cndmask_b32_e64 v8, 0, v8, s[6:7]
	v_cndmask_b32_e64 v9, 0, v9, s[6:7]
	v_cndmask_b32_e64 v10, 0, v10, s[6:7]
	v_cndmask_b32_e64 v11, 0, v11, s[6:7]
	ds_write_b128 v133, v[8:11] offset:26624
	s_waitcnt lgkmcnt(5)
	v_mfma_f32_16x16x32_bf16 v[108:111], v[248:251], v[212:215], v[108:111]
	v_mfma_f32_16x16x32_bf16 v[104:107], v[208:211], v[212:215], v[104:107]
	v_cndmask_b32_e64 v12, 0, v12, s[8:9]
	v_cndmask_b32_e64 v13, 0, v13, s[8:9]
	v_cndmask_b32_e64 v14, 0, v14, s[8:9]
	v_cndmask_b32_e64 v15, 0, v15, s[8:9]
	ds_write_b128 v133, v[12:15] offset:30720
	v_mfma_f32_16x16x32_bf16 v[100:103], v[232:235], v[212:215], v[100:103]
	v_mfma_f32_16x16x32_bf16 v[96:99], v[236:239], v[212:215], v[96:99]
	ds_write_b128 v133, v[16:19] offset:55296
	s_waitcnt lgkmcnt(6)
	v_mfma_f32_16x16x32_bf16 v[92:95], v[248:251], v[220:223], v[92:95]
	v_mfma_f32_16x16x32_bf16 v[88:91], v[208:211], v[220:223], v[88:91]
	ds_write_b128 v133, v[20:23] offset:59392
	v_mfma_f32_16x16x32_bf16 v[84:87], v[232:235], v[220:223], v[84:87]
	v_mfma_f32_16x16x32_bf16 v[80:83], v[236:239], v[220:223], v[80:83]
	ds_write_b128 v133, v[24:27] offset:63488
	s_waitcnt lgkmcnt(7)
	v_mfma_f32_16x16x32_bf16 v[76:79], v[248:251], v[224:227], v[76:79]
	v_mfma_f32_16x16x32_bf16 v[72:75], v[208:211], v[224:227], v[72:75]
	ds_write_b128 v135, v[32:35] offset:12288
	v_mfma_f32_16x16x32_bf16 v[68:71], v[232:235], v[224:227], v[68:71]
	v_mfma_f32_16x16x32_bf16 v[64:67], v[236:239], v[224:227], v[64:67]
	s_setprio 0
	s_cmp_gt_u32 s19, 12
	v_lshl_add_u64 v[164:165], v[146:147], 0, v[128:129]
	v_lshl_add_u64 v[162:163], v[148:149], 0, v[128:129]
	v_lshl_add_u64 v[160:161], v[150:151], 0, v[128:129]
	v_lshl_add_u64 v[158:159], v[152:153], 0, v[128:129]
	v_lshl_add_u64 v[156:157], v[154:155], 0, v[128:129]
	s_waitcnt lgkmcnt(0)
	s_barrier
	s_cbranch_scc1 .LBB0_333
	v_add_co_u32_e32 v20, vcc, 0x10000, v156
	global_load_dwordx4 v[0:3], v[164:165], off offset:384
	global_load_dwordx4 v[4:7], v[162:163], off offset:384
	global_load_dwordx4 v[8:11], v[160:161], off offset:384
	global_load_dwordx4 v[12:15], v[158:159], off offset:384
	global_load_dwordx4 v[16:19], v[156:157], off offset:384
	v_addc_co_u32_e32 v21, vcc, 0, v157, vcc
	v_add_co_u32_e32 v24, vcc, 0x20000, v156
	s_nop 1
	v_addc_co_u32_e32 v25, vcc, 0, v157, vcc
	v_add_co_u32_e32 v32, vcc, 0x30000, v156
	global_load_dwordx4 v[20:23], v[20:21], off offset:384
	s_nop 0
	global_load_dwordx4 v[24:27], v[24:25], off offset:384
	v_addc_co_u32_e32 v33, vcc, 0, v157, vcc
	global_load_dwordx4 v[32:35], v[32:33], off offset:384
; template <bool ATRANS = false, bool SWAP = true>
; DEV void gemm_seg(f32x4 (&acc)[4][4], bf16_t* As, bf16_t* Bs, const bf16_t* A, const bf16_t* B, int lda, int ldb,
;                   int K, int arow_lo, int arow_hi) {
;     ...
;   GLOAD(0, 0);
;   GLOAD(1, 1);
;   STAB(0, 0);
;   GLOAD(0, 2);
;   for (int kt = 0; kt < nk; kt += 2) {
;     COMPUTE(kt);
;     STAB(1, kt + 1);
;     GLOAD(1, kt + 3);
;     if (kt + 1 >= nk) break;
;     COMPUTE(kt + 1);
;     STAB(0, kt + 2);
.LBB0_333:
	s_setprio 1
	ds_read_b128 v[208:211], v137 offset:18432
	ds_read_b128 v[212:215], v139 offset:55296
	ds_read_b128 v[220:223], v139 offset:57344
	ds_read_b128 v[224:227], v139 offset:59392
	ds_read_b128 v[228:231], v139 offset:61440
	ds_read_b128 v[232:235], v137 offset:20480
	ds_read_b128 v[236:239], v137 offset:22528
	ds_read_b128 v[240:243], v137 offset:24576
	s_waitcnt lgkmcnt(6)
	v_mfma_f32_16x16x32_bf16 v[124:127], v[212:215], v[208:211], v[124:127]
	ds_read_b128 v[244:247], v145 offset:18432
	ds_read_b128 v[248:251], v207 offset:55296
	s_waitcnt lgkmcnt(7)
	v_mfma_f32_16x16x32_bf16 v[120:123], v[220:223], v[208:211], v[120:123]
	s_waitcnt lgkmcnt(6)
	v_mfma_f32_16x16x32_bf16 v[116:119], v[224:227], v[208:211], v[116:119]
	s_waitcnt lgkmcnt(5)
	v_mfma_f32_16x16x32_bf16 v[112:115], v[228:231], v[208:211], v[112:115]
	ds_read_b128 v[208:211], v207 offset:57344
	s_waitcnt lgkmcnt(5)
	v_mfma_f32_16x16x32_bf16 v[108:111], v[212:215], v[232:235], v[108:111]
	v_mfma_f32_16x16x32_bf16 v[104:107], v[220:223], v[232:235], v[104:107]
	v_mfma_f32_16x16x32_bf16 v[100:103], v[224:227], v[232:235], v[100:103]
	v_mfma_f32_16x16x32_bf16 v[96:99], v[228:231], v[232:235], v[96:99]
	ds_read_b128 v[232:235], v207 offset:59392
	s_waitcnt lgkmcnt(5)
	v_mfma_f32_16x16x32_bf16 v[92:95], v[212:215], v[236:239], v[92:95]
	v_mfma_f32_16x16x32_bf16 v[88:91], v[220:223], v[236:239], v[88:91]
	v_mfma_f32_16x16x32_bf16 v[84:87], v[224:227], v[236:239], v[84:87]
	v_mfma_f32_16x16x32_bf16 v[80:83], v[228:231], v[236:239], v[80:83]
	ds_read_b128 v[236:239], v207 offset:61440
	s_waitcnt lgkmcnt(5)
	v_mfma_f32_16x16x32_bf16 v[76:79], v[212:215], v[240:243], v[76:79]
	ds_read_b128 v[212:215], v145 offset:20480
	v_mfma_f32_16x16x32_bf16 v[72:75], v[220:223], v[240:243], v[72:75]
	ds_read_b128 v[220:223], v145 offset:22528
	v_mfma_f32_16x16x32_bf16 v[68:71], v[224:227], v[240:243], v[68:71]
	ds_read_b128 v[224:227], v145 offset:24576
	v_mfma_f32_16x16x32_bf16 v[64:67], v[228:231], v[240:243], v[64:67]
	s_waitcnt vmcnt(8)
	v_cndmask_b32_e64 v28, 0, v28, s[2:3]
	v_cndmask_b32_e64 v29, 0, v29, s[2:3]
	v_cndmask_b32_e64 v30, 0, v30, s[2:3]
	v_cndmask_b32_e64 v31, 0, v31, s[2:3]
	ds_write_b128 v133, v[28:31]
	s_waitcnt lgkmcnt(7)
	v_mfma_f32_16x16x32_bf16 v[124:127], v[248:251], v[244:247], v[124:127]
	s_waitcnt lgkmcnt(6)
	v_mfma_f32_16x16x32_bf16 v[120:123], v[208:211], v[244:247], v[120:123]
	v_cndmask_b32_e64 v36, 0, v36, s[4:5]
	v_cndmask_b32_e64 v37, 0, v37, s[4:5]
	v_cndmask_b32_e64 v38, 0, v38, s[4:5]
	v_cndmask_b32_e64 v39, 0, v39, s[4:5]
	ds_write_b128 v133, v[36:39] offset:4096
	s_waitcnt lgkmcnt(6)
	v_mfma_f32_16x16x32_bf16 v[116:119], v[232:235], v[244:247], v[116:119]
	s_waitcnt lgkmcnt(5)
	v_mfma_f32_16x16x32_bf16 v[112:115], v[236:239], v[244:247], v[112:115]
	v_cndmask_b32_e64 v40, 0, v40, s[6:7]
	v_cndmask_b32_e64 v41, 0, v41, s[6:7]
	v_cndmask_b32_e64 v42, 0, v42, s[6:7]
	v_cndmask_b32_e64 v43, 0, v43, s[6:7]
	ds_write_b128 v133, v[40:43] offset:8192
	s_waitcnt lgkmcnt(5)
	v_mfma_f32_16x16x32_bf16 v[108:111], v[248:251], v[212:215], v[108:111]
	v_mfma_f32_16x16x32_bf16 v[104:107], v[208:211], v[212:215], v[104:107]
	v_cndmask_b32_e64 v44, 0, v44, s[8:9]
	v_cndmask_b32_e64 v45, 0, v45, s[8:9]
	v_cndmask_b32_e64 v46, 0, v46, s[8:9]
	v_cndmask_b32_e64 v47, 0, v47, s[8:9]
	ds_write_b128 v133, v[44:47] offset:12288
	v_mfma_f32_16x16x32_bf16 v[100:103], v[232:235], v[212:215], v[100:103]
	v_mfma_f32_16x16x32_bf16 v[96:99], v[236:239], v[212:215], v[96:99]
	ds_write_b128 v133, v[48:51] offset:36864
	s_waitcnt lgkmcnt(6)
	v_mfma_f32_16x16x32_bf16 v[92:95], v[248:251], v[220:223], v[92:95]
	v_mfma_f32_16x16x32_bf16 v[88:91], v[208:211], v[220:223], v[88:91]
	ds_write_b128 v133, v[52:55] offset:40960
	v_mfma_f32_16x16x32_bf16 v[84:87], v[232:235], v[220:223], v[84:87]
	v_mfma_f32_16x16x32_bf16 v[80:83], v[236:239], v[220:223], v[80:83]
	ds_write_b128 v133, v[56:59] offset:45056
	s_waitcnt lgkmcnt(7)
	v_mfma_f32_16x16x32_bf16 v[76:79], v[248:251], v[224:227], v[76:79]
	v_mfma_f32_16x16x32_bf16 v[72:75], v[208:211], v[224:227], v[72:75]
	ds_write_b128 v133, v[60:63] offset:49152
	v_mfma_f32_16x16x32_bf16 v[68:71], v[232:235], v[224:227], v[68:71]
	v_mfma_f32_16x16x32_bf16 v[64:67], v[236:239], v[224:227], v[64:67]
	s_setprio 0
	s_cmp_gt_u32 s19, 13
	s_cselect_b64 s[22:23], -1, 0

; template <bool ATRANS = false, bool SWAP = true>
; DEV void gemm_seg(f32x4 (&acc)[4][4], bf16_t* As, bf16_t* Bs, const bf16_t* A, const bf16_t* B, int lda, int ldb,
;                   int K, int arow_lo, int arow_hi) {
;     ...
;   GLOAD(0, 0);
;   GLOAD(1, 1);
;   STAB(0, 0);
;   GLOAD(0, 2);
;   for (int kt = 0; kt < nk; kt += 2) {
;     COMPUTE(kt);
;     STAB(1, kt + 1);
;     GLOAD(1, kt + 3);
;     if (kt + 1 >= nk) break;
;     COMPUTE(kt + 1);
;     STAB(0, kt + 2);
;     GLOAD(0, kt + 4);
.Lvm_win2_ok:
	s_setprio 1
	ds_read_b128 v[208:211], v139 offset:36864
	ds_read_b128 v[212:215], v137
	ds_read_b128 v[220:223], v137 offset:2048
	ds_read_b128 v[224:227], v137 offset:4096
	ds_read_b128 v[228:231], v137 offset:6144
	ds_read_b128 v[232:235], v139 offset:38912
	ds_read_b128 v[236:239], v139 offset:40960
	ds_read_b128 v[240:243], v139 offset:43008
	s_waitcnt lgkmcnt(6)
	v_mfma_f32_16x16x32_bf16 v[124:127], v[212:215], v[208:211], v[124:127]
	ds_read_b128 v[244:247], v207 offset:43008
	ds_read_b128 v[248:251], v145
	s_waitcnt lgkmcnt(7)
	v_mfma_f32_16x16x32_bf16 v[108:111], v[220:223], v[208:211], v[108:111]
	s_waitcnt lgkmcnt(6)
	v_mfma_f32_16x16x32_bf16 v[92:95], v[224:227], v[208:211], v[92:95]
	s_waitcnt lgkmcnt(5)
	v_mfma_f32_16x16x32_bf16 v[76:79], v[228:231], v[208:211], v[76:79]
	ds_read_b128 v[208:211], v145 offset:2048
	s_waitcnt lgkmcnt(5)
	v_mfma_f32_16x16x32_bf16 v[120:123], v[212:215], v[232:235], v[120:123]
	v_mfma_f32_16x16x32_bf16 v[104:107], v[220:223], v[232:235], v[104:107]
	v_mfma_f32_16x16x32_bf16 v[88:91], v[224:227], v[232:235], v[88:91]
	v_mfma_f32_16x16x32_bf16 v[72:75], v[228:231], v[232:235], v[72:75]
	ds_read_b128 v[232:235], v145 offset:4096
	s_waitcnt lgkmcnt(5)
	v_mfma_f32_16x16x32_bf16 v[116:119], v[212:215], v[236:239], v[116:119]
	v_mfma_f32_16x16x32_bf16 v[100:103], v[220:223], v[236:239], v[100:103]
	v_mfma_f32_16x16x32_bf16 v[84:87], v[224:227], v[236:239], v[84:87]
	v_mfma_f32_16x16x32_bf16 v[68:71], v[228:231], v[236:239], v[68:71]
	ds_read_b128 v[236:239], v145 offset:6144
	s_waitcnt lgkmcnt(5)
	v_mfma_f32_16x16x32_bf16 v[112:115], v[212:215], v[240:243], v[112:115]
	ds_read_b128 v[212:215], v207 offset:36864
	v_mfma_f32_16x16x32_bf16 v[96:99], v[220:223], v[240:243], v[96:99]
	ds_read_b128 v[220:223], v207 offset:38912
	v_mfma_f32_16x16x32_bf16 v[80:83], v[224:227], v[240:243], v[80:83]
	ds_read_b128 v[224:227], v207 offset:40960
	v_mfma_f32_16x16x32_bf16 v[64:67], v[228:231], v[240:243], v[64:67]
	s_waitcnt vmcnt(8)
	v_cndmask_b32_e64 v0, 0, v0, s[2:3]
	v_cndmask_b32_e64 v1, 0, v1, s[2:3]
	v_cndmask_b32_e64 v2, 0, v2, s[2:3]
	v_cndmask_b32_e64 v3, 0, v3, s[2:3]
	ds_write_b128 v133, v[0:3] offset:18432
	s_waitcnt lgkmcnt(7)
	v_mfma_f32_16x16x32_bf16 v[112:115], v[248:251], v[244:247], v[112:115]
	s_waitcnt lgkmcnt(6)
	v_mfma_f32_16x16x32_bf16 v[96:99], v[208:211], v[244:247], v[96:99]
	v_cndmask_b32_e64 v4, 0, v4, s[4:5]
	v_cndmask_b32_e64 v5, 0, v5, s[4:5]
	v_cndmask_b32_e64 v6, 0, v6, s[4:5]
	v_cndmask_b32_e64 v7, 0, v7, s[4:5]
	ds_write_b128 v133, v[4:7] offset:22528
	s_waitcnt lgkmcnt(6)
	v_mfma_f32_16x16x32_bf16 v[80:83], v[232:235], v[244:247], v[80:83]
	s_waitcnt lgkmcnt(5)
	v_mfma_f32_16x16x32_bf16 v[64:67], v[236:239], v[244:247], v[64:67]
	v_cndmask_b32_e64 v8, 0, v8, s[6:7]
	v_cndmask_b32_e64 v9, 0, v9, s[6:7]
	v_cndmask_b32_e64 v10, 0, v10, s[6:7]
	v_cndmask_b32_e64 v11, 0, v11, s[6:7]
	ds_write_b128 v133, v[8:11] offset:26624
	s_waitcnt lgkmcnt(5)
	v_mfma_f32_16x16x32_bf16 v[124:127], v[248:251], v[212:215], v[124:127]
	v_mfma_f32_16x16x32_bf16 v[108:111], v[208:211], v[212:215], v[108:111]
	v_cndmask_b32_e64 v12, 0, v12, s[8:9]
	v_cndmask_b32_e64 v13, 0, v13, s[8:9]
	v_cndmask_b32_e64 v14, 0, v14, s[8:9]
	v_cndmask_b32_e64 v15, 0, v15, s[8:9]
	ds_write_b128 v133, v[12:15] offset:30720
	v_mfma_f32_16x16x32_bf16 v[92:95], v[232:235], v[212:215], v[92:95]
	v_mfma_f32_16x16x32_bf16 v[76:79], v[236:239], v[212:215], v[76:79]
	ds_write_b128 v133, v[16:19] offset:55296
	s_waitcnt lgkmcnt(6)
	v_mfma_f32_16x16x32_bf16 v[120:123], v[248:251], v[220:223], v[120:123]
	v_mfma_f32_16x16x32_bf16 v[104:107], v[208:211], v[220:223], v[104:107]
	ds_write_b128 v133, v[20:23] offset:59392
	v_mfma_f32_16x16x32_bf16 v[88:91], v[232:235], v[220:223], v[88:91]
	v_mfma_f32_16x16x32_bf16 v[72:75], v[236:239], v[220:223], v[72:75]
	ds_write_b128 v133, v[24:27] offset:63488
	s_waitcnt lgkmcnt(7)
	v_mfma_f32_16x16x32_bf16 v[116:119], v[248:251], v[224:227], v[116:119]
	v_mfma_f32_16x16x32_bf16 v[100:103], v[208:211], v[224:227], v[100:103]
	ds_write_b128 v135, v[28:31] offset:12288
	v_mfma_f32_16x16x32_bf16 v[84:87], v[232:235], v[224:227], v[84:87]
	v_mfma_f32_16x16x32_bf16 v[68:71], v[236:239], v[224:227], v[68:71]
	s_setprio 0
	s_cmp_gt_u32 s19, 12
	v_lshl_add_u64 v[164:165], v[146:147], 0, v[128:129]
	v_lshl_add_u64 v[162:163], v[148:149], 0, v[128:129]
	v_lshl_add_u64 v[160:161], v[150:151], 0, v[128:129]
	v_lshl_add_u64 v[158:159], v[152:153], 0, v[128:129]
	v_lshl_add_u64 v[156:157], v[154:155], 0, v[128:129]
	s_waitcnt lgkmcnt(0)
	s_barrier
	s_cbranch_scc1 .LBB0_343
	v_add_co_u32_e32 v20, vcc, 0x10000, v156
	global_load_dwordx4 v[0:3], v[164:165], off offset:384
	global_load_dwordx4 v[4:7], v[162:163], off offset:384
	global_load_dwordx4 v[8:11], v[160:161], off offset:384
	global_load_dwordx4 v[12:15], v[158:159], off offset:384
	global_load_dwordx4 v[16:19], v[156:157], off offset:384
	v_addc_co_u32_e32 v21, vcc, 0, v157, vcc
	v_add_co_u32_e32 v24, vcc, 0x20000, v156
	s_nop 1
	v_addc_co_u32_e32 v25, vcc, 0, v157, vcc
	v_add_co_u32_e32 v28, vcc, 0x30000, v156
	global_load_dwordx4 v[20:23], v[20:21], off offset:384
	s_nop 0
	global_load_dwordx4 v[24:27], v[24:25], off offset:384
	v_addc_co_u32_e32 v29, vcc, 0, v157, vcc
	global_load_dwordx4 v[28:31], v[28:29], off offset:384
; template <bool ATRANS = false, bool SWAP = true>
; DEV void gemm_seg(f32x4 (&acc)[4][4], bf16_t* As, bf16_t* Bs, const bf16_t* A, const bf16_t* B, int lda, int ldb,
;                   int K, int arow_lo, int arow_hi) {
;     ...
;   GLOAD(0, 0);
;   GLOAD(1, 1);
;   STAB(0, 0);
;   GLOAD(0, 2);
;   for (int kt = 0; kt < nk; kt += 2) {
;     COMPUTE(kt);
;     STAB(1, kt + 1);
;     GLOAD(1, kt + 3);
;     if (kt + 1 >= nk) break;
;     COMPUTE(kt + 1);
;     STAB(0, kt + 2);
.LBB0_343:
	s_setprio 1
	ds_read_b128 v[208:211], v139 offset:55296
	ds_read_b128 v[212:215], v137 offset:18432
	ds_read_b128 v[220:223], v137 offset:20480
	ds_read_b128 v[224:227], v137 offset:22528
	ds_read_b128 v[228:231], v137 offset:24576
	ds_read_b128 v[232:235], v139 offset:57344
	ds_read_b128 v[236:239], v139 offset:59392
	ds_read_b128 v[240:243], v139 offset:61440
	s_waitcnt lgkmcnt(6)
	v_mfma_f32_16x16x32_bf16 v[124:127], v[212:215], v[208:211], v[124:127]
	ds_read_b128 v[244:247], v207 offset:55296
	ds_read_b128 v[248:251], v145 offset:18432
	s_waitcnt lgkmcnt(7)
	v_mfma_f32_16x16x32_bf16 v[108:111], v[220:223], v[208:211], v[108:111]
	s_waitcnt lgkmcnt(6)
	v_mfma_f32_16x16x32_bf16 v[92:95], v[224:227], v[208:211], v[92:95]
	s_waitcnt lgkmcnt(5)
	v_mfma_f32_16x16x32_bf16 v[76:79], v[228:231], v[208:211], v[76:79]
	ds_read_b128 v[208:211], v145 offset:20480
	s_waitcnt lgkmcnt(5)
	v_mfma_f32_16x16x32_bf16 v[120:123], v[212:215], v[232:235], v[120:123]
	v_mfma_f32_16x16x32_bf16 v[104:107], v[220:223], v[232:235], v[104:107]
	v_mfma_f32_16x16x32_bf16 v[88:91], v[224:227], v[232:235], v[88:91]
	v_mfma_f32_16x16x32_bf16 v[72:75], v[228:231], v[232:235], v[72:75]
	ds_read_b128 v[232:235], v145 offset:22528
	s_waitcnt lgkmcnt(5)
	v_mfma_f32_16x16x32_bf16 v[116:119], v[212:215], v[236:239], v[116:119]
	v_mfma_f32_16x16x32_bf16 v[100:103], v[220:223], v[236:239], v[100:103]
	v_mfma_f32_16x16x32_bf16 v[84:87], v[224:227], v[236:239], v[84:87]
	v_mfma_f32_16x16x32_bf16 v[68:71], v[228:231], v[236:239], v[68:71]
	ds_read_b128 v[236:239], v145 offset:24576
	s_waitcnt lgkmcnt(5)
	v_mfma_f32_16x16x32_bf16 v[112:115], v[212:215], v[240:243], v[112:115]
	ds_read_b128 v[212:215], v207 offset:57344
	v_mfma_f32_16x16x32_bf16 v[96:99], v[220:223], v[240:243], v[96:99]
	ds_read_b128 v[220:223], v207 offset:59392
	v_mfma_f32_16x16x32_bf16 v[80:83], v[224:227], v[240:243], v[80:83]
	ds_read_b128 v[224:227], v207 offset:61440
	v_mfma_f32_16x16x32_bf16 v[64:67], v[228:231], v[240:243], v[64:67]
	s_waitcnt vmcnt(8)
	v_cndmask_b32_e64 v32, 0, v32, s[2:3]
	v_cndmask_b32_e64 v33, 0, v33, s[2:3]
	v_cndmask_b32_e64 v34, 0, v34, s[2:3]
	v_cndmask_b32_e64 v35, 0, v35, s[2:3]
	ds_write_b128 v133, v[32:35]
	s_waitcnt lgkmcnt(7)
	v_mfma_f32_16x16x32_bf16 v[124:127], v[248:251], v[244:247], v[124:127]
	s_waitcnt lgkmcnt(6)
	v_mfma_f32_16x16x32_bf16 v[108:111], v[208:211], v[244:247], v[108:111]
	v_cndmask_b32_e64 v36, 0, v36, s[4:5]
	v_cndmask_b32_e64 v37, 0, v37, s[4:5]
	v_cndmask_b32_e64 v38, 0, v38, s[4:5]
	v_cndmask_b32_e64 v39, 0, v39, s[4:5]
	ds_write_b128 v133, v[36:39] offset:4096
	s_waitcnt lgkmcnt(6)
	v_mfma_f32_16x16x32_bf16 v[92:95], v[232:235], v[244:247], v[92:95]
	s_waitcnt lgkmcnt(5)
	v_mfma_f32_16x16x32_bf16 v[76:79], v[236:239], v[244:247], v[76:79]
	v_cndmask_b32_e64 v40, 0, v40, s[6:7]
	v_cndmask_b32_e64 v41, 0, v41, s[6:7]
	v_cndmask_b32_e64 v42, 0, v42, s[6:7]
	v_cndmask_b32_e64 v43, 0, v43, s[6:7]
	ds_write_b128 v133, v[40:43] offset:8192
	s_waitcnt lgkmcnt(5)
	v_mfma_f32_16x16x32_bf16 v[120:123], v[248:251], v[212:215], v[120:123]
	v_mfma_f32_16x16x32_bf16 v[104:107], v[208:211], v[212:215], v[104:107]
	v_cndmask_b32_e64 v44, 0, v44, s[8:9]
	v_cndmask_b32_e64 v45, 0, v45, s[8:9]
	v_cndmask_b32_e64 v46, 0, v46, s[8:9]
	v_cndmask_b32_e64 v47, 0, v47, s[8:9]
	ds_write_b128 v133, v[44:47] offset:12288
	v_mfma_f32_16x16x32_bf16 v[88:91], v[232:235], v[212:215], v[88:91]
	v_mfma_f32_16x16x32_bf16 v[72:75], v[236:239], v[212:215], v[72:75]
	ds_write_b128 v133, v[48:51] offset:36864
	s_waitcnt lgkmcnt(6)
	v_mfma_f32_16x16x32_bf16 v[116:119], v[248:251], v[220:223], v[116:119]
	v_mfma_f32_16x16x32_bf16 v[100:103], v[208:211], v[220:223], v[100:103]
	ds_write_b128 v133, v[52:55] offset:40960
	v_mfma_f32_16x16x32_bf16 v[84:87], v[232:235], v[220:223], v[84:87]
	v_mfma_f32_16x16x32_bf16 v[68:71], v[236:239], v[220:223], v[68:71]
	ds_write_b128 v133, v[56:59] offset:45056
	s_waitcnt lgkmcnt(7)
	v_mfma_f32_16x16x32_bf16 v[112:115], v[248:251], v[224:227], v[112:115]
	v_mfma_f32_16x16x32_bf16 v[96:99], v[208:211], v[224:227], v[96:99]
	ds_write_b128 v133, v[60:63] offset:49152
	v_mfma_f32_16x16x32_bf16 v[80:83], v[232:235], v[224:227], v[80:83]
	v_mfma_f32_16x16x32_bf16 v[64:67], v[236:239], v[224:227], v[64:67]
	s_setprio 0
	s_cmp_gt_u32 s19, 13
	s_cselect_b64 s[0:1], -1, 0

; template <bool ATRANS = false, bool SWAP = true>
; DEV void gemm_seg(f32x4 (&acc)[4][4], bf16_t* As, bf16_t* Bs, const bf16_t* A, const bf16_t* B, int lda, int ldb,
;                   int K, int arow_lo, int arow_hi) {
;     ...
;   GLOAD(0, 0);
;   GLOAD(1, 1);
;   STAB(0, 0);
;   GLOAD(0, 2);
;   for (int kt = 0; kt < nk; kt += 2) {
;     COMPUTE(kt);
;     STAB(1, kt + 1);
;     GLOAD(1, kt + 3);
;     if (kt + 1 >= nk) break;
;     COMPUTE(kt + 1);
;     STAB(0, kt + 2);
;     GLOAD(0, kt + 4);
.Lvm_up_ok:
	s_setprio 1
	ds_read_b128 v[168:171], v139
	ds_read_b128 v[208:211], v164 offset:36864
	ds_read_b128 v[212:215], v164 offset:38912
	ds_read_b128 v[220:223], v164 offset:40960
	ds_read_b128 v[224:227], v164 offset:43008
	ds_read_b128 v[228:231], v139 offset:2048
	ds_read_b128 v[232:235], v139 offset:4096
	ds_read_b128 v[236:239], v139 offset:6144
	s_waitcnt lgkmcnt(6)
	v_mfma_f32_16x16x32_bf16 v[124:127], v[208:211], v[168:171], v[124:127]
	ds_read_b128 v[240:243], v165
	ds_read_b128 v[244:247], v207 offset:36864
	s_waitcnt lgkmcnt(7)
	v_mfma_f32_16x16x32_bf16 v[120:123], v[212:215], v[168:171], v[120:123]
	s_waitcnt lgkmcnt(6)
	v_mfma_f32_16x16x32_bf16 v[116:119], v[220:223], v[168:171], v[116:119]
	s_waitcnt lgkmcnt(5)
	v_mfma_f32_16x16x32_bf16 v[112:115], v[224:227], v[168:171], v[112:115]
	ds_read_b128 v[168:171], v207 offset:38912
	s_waitcnt lgkmcnt(5)
	v_mfma_f32_16x16x32_bf16 v[108:111], v[208:211], v[228:231], v[108:111]
	v_mfma_f32_16x16x32_bf16 v[104:107], v[212:215], v[228:231], v[104:107]
	v_mfma_f32_16x16x32_bf16 v[100:103], v[220:223], v[228:231], v[100:103]
	v_mfma_f32_16x16x32_bf16 v[96:99], v[224:227], v[228:231], v[96:99]
	ds_read_b128 v[228:231], v207 offset:40960
	s_waitcnt lgkmcnt(5)
	v_mfma_f32_16x16x32_bf16 v[92:95], v[208:211], v[232:235], v[92:95]
	v_mfma_f32_16x16x32_bf16 v[88:91], v[212:215], v[232:235], v[88:91]
	v_mfma_f32_16x16x32_bf16 v[84:87], v[220:223], v[232:235], v[84:87]
	v_mfma_f32_16x16x32_bf16 v[80:83], v[224:227], v[232:235], v[80:83]
	ds_read_b128 v[232:235], v207 offset:43008
	s_waitcnt lgkmcnt(5)
	v_mfma_f32_16x16x32_bf16 v[76:79], v[208:211], v[236:239], v[76:79]
	ds_read_b128 v[208:211], v165 offset:2048
	v_mfma_f32_16x16x32_bf16 v[72:75], v[212:215], v[236:239], v[72:75]
	ds_read_b128 v[212:215], v165 offset:4096
	v_mfma_f32_16x16x32_bf16 v[68:71], v[220:223], v[236:239], v[68:71]
	ds_read_b128 v[220:223], v165 offset:6144
	v_mfma_f32_16x16x32_bf16 v[64:67], v[224:227], v[236:239], v[64:67]
	s_waitcnt vmcnt(8)
	v_cndmask_b32_e64 v0, 0, v0, s[2:3]
	v_cndmask_b32_e64 v1, 0, v1, s[2:3]
	v_cndmask_b32_e64 v2, 0, v2, s[2:3]
	v_cndmask_b32_e64 v3, 0, v3, s[2:3]
	ds_write_b128 v135, v[0:3] offset:18432
	s_waitcnt lgkmcnt(7)
	v_mfma_f32_16x16x32_bf16 v[124:127], v[244:247], v[240:243], v[124:127]
	s_waitcnt lgkmcnt(6)
	v_mfma_f32_16x16x32_bf16 v[120:123], v[168:171], v[240:243], v[120:123]
	v_cndmask_b32_e64 v4, 0, v4, s[4:5]
	v_cndmask_b32_e64 v5, 0, v5, s[4:5]
	v_cndmask_b32_e64 v6, 0, v6, s[4:5]
	v_cndmask_b32_e64 v7, 0, v7, s[4:5]
	ds_write_b128 v135, v[4:7] offset:22528
	s_waitcnt lgkmcnt(6)
	v_mfma_f32_16x16x32_bf16 v[116:119], v[228:231], v[240:243], v[116:119]
	s_waitcnt lgkmcnt(5)
	v_mfma_f32_16x16x32_bf16 v[112:115], v[232:235], v[240:243], v[112:115]
	v_cndmask_b32_e64 v8, 0, v8, s[6:7]
	v_cndmask_b32_e64 v9, 0, v9, s[6:7]
	v_cndmask_b32_e64 v10, 0, v10, s[6:7]
	v_cndmask_b32_e64 v11, 0, v11, s[6:7]
	ds_write_b128 v135, v[8:11] offset:26624
	s_waitcnt lgkmcnt(5)
	v_mfma_f32_16x16x32_bf16 v[108:111], v[244:247], v[208:211], v[108:111]
	v_mfma_f32_16x16x32_bf16 v[104:107], v[168:171], v[208:211], v[104:107]
	v_cndmask_b32_e64 v12, 0, v12, s[8:9]
	v_cndmask_b32_e64 v13, 0, v13, s[8:9]
	v_cndmask_b32_e64 v14, 0, v14, s[8:9]
	v_cndmask_b32_e64 v15, 0, v15, s[8:9]
	ds_write_b128 v135, v[12:15] offset:30720
	v_mfma_f32_16x16x32_bf16 v[100:103], v[228:231], v[208:211], v[100:103]
	v_mfma_f32_16x16x32_bf16 v[96:99], v[232:235], v[208:211], v[96:99]
	ds_write_b128 v135, v[16:19] offset:55296
	s_waitcnt lgkmcnt(6)
	v_mfma_f32_16x16x32_bf16 v[92:95], v[244:247], v[212:215], v[92:95]
	v_mfma_f32_16x16x32_bf16 v[88:91], v[168:171], v[212:215], v[88:91]
	ds_write_b128 v135, v[20:23] offset:59392
	v_mfma_f32_16x16x32_bf16 v[84:87], v[228:231], v[212:215], v[84:87]
	v_mfma_f32_16x16x32_bf16 v[80:83], v[232:235], v[212:215], v[80:83]
	ds_write_b128 v135, v[24:27] offset:63488
	s_waitcnt lgkmcnt(7)
	v_mfma_f32_16x16x32_bf16 v[76:79], v[244:247], v[220:223], v[76:79]
	v_mfma_f32_16x16x32_bf16 v[72:75], v[168:171], v[220:223], v[72:75]
	ds_write_b128 v137, v[32:35] offset:12288
	v_mfma_f32_16x16x32_bf16 v[68:71], v[228:231], v[220:223], v[68:71]
	v_mfma_f32_16x16x32_bf16 v[64:67], v[232:235], v[220:223], v[64:67]
	s_setprio 0
	s_cmp_gt_u32 s22, 12
	v_lshl_add_u64 v[162:163], v[146:147], 0, v[128:129]
	v_lshl_add_u64 v[160:161], v[148:149], 0, v[128:129]
	v_lshl_add_u64 v[158:159], v[150:151], 0, v[128:129]
	v_lshl_add_u64 v[156:157], v[152:153], 0, v[128:129]
	v_lshl_add_u64 v[154:155], v[144:145], 0, v[128:129]
	s_waitcnt lgkmcnt(0)
	s_barrier
	s_cbranch_scc1 .LBB0_826
	v_add_co_u32_e32 v20, vcc, 0x10000, v154
	global_load_dwordx4 v[0:3], v[162:163], off
	global_load_dwordx4 v[4:7], v[160:161], off
	global_load_dwordx4 v[8:11], v[158:159], off
	global_load_dwordx4 v[12:15], v[156:157], off
	global_load_dwordx4 v[16:19], v[154:155], off offset:384
	v_addc_co_u32_e32 v21, vcc, 0, v155, vcc
	v_add_co_u32_e32 v24, vcc, 0x20000, v154
	s_nop 1
	v_addc_co_u32_e32 v25, vcc, 0, v155, vcc
	v_add_co_u32_e32 v32, vcc, 0x30000, v154
	global_load_dwordx4 v[20:23], v[20:21], off offset:384
	s_nop 0
	global_load_dwordx4 v[24:27], v[24:25], off offset:384
	v_addc_co_u32_e32 v33, vcc, 0, v155, vcc
	global_load_dwordx4 v[32:35], v[32:33], off offset:384
; template <bool ATRANS = false, bool SWAP = true>
; DEV void gemm_seg(f32x4 (&acc)[4][4], bf16_t* As, bf16_t* Bs, const bf16_t* A, const bf16_t* B, int lda, int ldb,
;                   int K, int arow_lo, int arow_hi) {
;     ...
;   GLOAD(0, 0);
;   GLOAD(1, 1);
;   STAB(0, 0);
;   GLOAD(0, 2);
;   for (int kt = 0; kt < nk; kt += 2) {
;     COMPUTE(kt);
;     STAB(1, kt + 1);
;     GLOAD(1, kt + 3);
;     if (kt + 1 >= nk) break;
;     COMPUTE(kt + 1);
;     STAB(0, kt + 2);
.LBB0_826:
	s_setprio 1
	ds_read_b128 v[168:171], v139 offset:18432
	ds_read_b128 v[208:211], v164 offset:55296
	ds_read_b128 v[212:215], v164 offset:57344
	ds_read_b128 v[220:223], v164 offset:59392
	ds_read_b128 v[224:227], v164 offset:61440
	ds_read_b128 v[228:231], v139 offset:20480
	ds_read_b128 v[232:235], v139 offset:22528
	ds_read_b128 v[236:239], v139 offset:24576
	s_waitcnt lgkmcnt(6)
	v_mfma_f32_16x16x32_bf16 v[124:127], v[208:211], v[168:171], v[124:127]
	ds_read_b128 v[240:243], v165 offset:18432
	ds_read_b128 v[244:247], v207 offset:55296
	s_waitcnt lgkmcnt(7)
	v_mfma_f32_16x16x32_bf16 v[120:123], v[212:215], v[168:171], v[120:123]
	s_waitcnt lgkmcnt(6)
	v_mfma_f32_16x16x32_bf16 v[116:119], v[220:223], v[168:171], v[116:119]
	s_waitcnt lgkmcnt(5)
	v_mfma_f32_16x16x32_bf16 v[112:115], v[224:227], v[168:171], v[112:115]
	ds_read_b128 v[168:171], v207 offset:57344
	s_waitcnt lgkmcnt(5)
	v_mfma_f32_16x16x32_bf16 v[108:111], v[208:211], v[228:231], v[108:111]
	v_mfma_f32_16x16x32_bf16 v[104:107], v[212:215], v[228:231], v[104:107]
	v_mfma_f32_16x16x32_bf16 v[100:103], v[220:223], v[228:231], v[100:103]
	v_mfma_f32_16x16x32_bf16 v[96:99], v[224:227], v[228:231], v[96:99]
	ds_read_b128 v[228:231], v207 offset:59392
	s_waitcnt lgkmcnt(5)
	v_mfma_f32_16x16x32_bf16 v[92:95], v[208:211], v[232:235], v[92:95]
	v_mfma_f32_16x16x32_bf16 v[88:91], v[212:215], v[232:235], v[88:91]
	v_mfma_f32_16x16x32_bf16 v[84:87], v[220:223], v[232:235], v[84:87]
	v_mfma_f32_16x16x32_bf16 v[80:83], v[224:227], v[232:235], v[80:83]
	ds_read_b128 v[232:235], v207 offset:61440
	s_waitcnt lgkmcnt(5)
	v_mfma_f32_16x16x32_bf16 v[76:79], v[208:211], v[236:239], v[76:79]
	ds_read_b128 v[208:211], v165 offset:20480
	v_mfma_f32_16x16x32_bf16 v[72:75], v[212:215], v[236:239], v[72:75]
	ds_read_b128 v[212:215], v165 offset:22528
	v_mfma_f32_16x16x32_bf16 v[68:71], v[220:223], v[236:239], v[68:71]
	ds_read_b128 v[220:223], v165 offset:24576
	v_mfma_f32_16x16x32_bf16 v[64:67], v[224:227], v[236:239], v[64:67]
	s_waitcnt vmcnt(8)
	v_cndmask_b32_e64 v28, 0, v28, s[2:3]
	v_cndmask_b32_e64 v29, 0, v29, s[2:3]
	v_cndmask_b32_e64 v30, 0, v30, s[2:3]
	v_cndmask_b32_e64 v31, 0, v31, s[2:3]
	ds_write_b128 v135, v[28:31]
	s_waitcnt lgkmcnt(7)
	v_mfma_f32_16x16x32_bf16 v[124:127], v[244:247], v[240:243], v[124:127]
	s_waitcnt lgkmcnt(6)
	v_mfma_f32_16x16x32_bf16 v[120:123], v[168:171], v[240:243], v[120:123]
	v_cndmask_b32_e64 v36, 0, v36, s[4:5]
	v_cndmask_b32_e64 v37, 0, v37, s[4:5]
	v_cndmask_b32_e64 v38, 0, v38, s[4:5]
	v_cndmask_b32_e64 v39, 0, v39, s[4:5]
	ds_write_b128 v135, v[36:39] offset:4096
	s_waitcnt lgkmcnt(6)
	v_mfma_f32_16x16x32_bf16 v[116:119], v[228:231], v[240:243], v[116:119]
	s_waitcnt lgkmcnt(5)
	v_mfma_f32_16x16x32_bf16 v[112:115], v[232:235], v[240:243], v[112:115]
	v_cndmask_b32_e64 v40, 0, v40, s[6:7]
	v_cndmask_b32_e64 v41, 0, v41, s[6:7]
	v_cndmask_b32_e64 v42, 0, v42, s[6:7]
	v_cndmask_b32_e64 v43, 0, v43, s[6:7]
	ds_write_b128 v135, v[40:43] offset:8192
	s_waitcnt lgkmcnt(5)
	v_mfma_f32_16x16x32_bf16 v[108:111], v[244:247], v[208:211], v[108:111]
	v_mfma_f32_16x16x32_bf16 v[104:107], v[168:171], v[208:211], v[104:107]
	v_cndmask_b32_e64 v44, 0, v44, s[8:9]
	v_cndmask_b32_e64 v45, 0, v45, s[8:9]
	v_cndmask_b32_e64 v46, 0, v46, s[8:9]
	v_cndmask_b32_e64 v47, 0, v47, s[8:9]
	ds_write_b128 v135, v[44:47] offset:12288
	v_mfma_f32_16x16x32_bf16 v[100:103], v[228:231], v[208:211], v[100:103]
	v_mfma_f32_16x16x32_bf16 v[96:99], v[232:235], v[208:211], v[96:99]
	ds_write_b128 v135, v[48:51] offset:36864
	s_waitcnt lgkmcnt(6)
	v_mfma_f32_16x16x32_bf16 v[92:95], v[244:247], v[212:215], v[92:95]
	v_mfma_f32_16x16x32_bf16 v[88:91], v[168:171], v[212:215], v[88:91]
	ds_write_b128 v135, v[52:55] offset:40960
	v_mfma_f32_16x16x32_bf16 v[84:87], v[228:231], v[212:215], v[84:87]
	v_mfma_f32_16x16x32_bf16 v[80:83], v[232:235], v[212:215], v[80:83]
	ds_write_b128 v135, v[56:59] offset:45056
	s_waitcnt lgkmcnt(7)
	v_mfma_f32_16x16x32_bf16 v[76:79], v[244:247], v[220:223], v[76:79]
	v_mfma_f32_16x16x32_bf16 v[72:75], v[168:171], v[220:223], v[72:75]
	ds_write_b128 v135, v[60:63] offset:49152
	v_mfma_f32_16x16x32_bf16 v[68:71], v[228:231], v[220:223], v[68:71]
	v_mfma_f32_16x16x32_bf16 v[64:67], v[232:235], v[220:223], v[64:67]
	s_setprio 0
	s_cmp_gt_u32 s22, 13
	s_cselect_b64 s[0:1], -1, 0

; template <bool ATRANS = false, bool SWAP = true>
; DEV void gemm_seg(f32x4 (&acc)[4][4], bf16_t* As, bf16_t* Bs, const bf16_t* A, const bf16_t* B, int lda, int ldb,
;                   int K, int arow_lo, int arow_hi) {
;     ...
;   GLOAD(0, 0);
;   GLOAD(1, 1);
;   STAB(0, 0);
;   GLOAD(0, 2);
;   for (int kt = 0; kt < nk; kt += 2) {
;     COMPUTE(kt);
;     STAB(1, kt + 1);
;     GLOAD(1, kt + 3);
;     if (kt + 1 >= nk) break;
;     COMPUTE(kt + 1);
;     STAB(0, kt + 2);
;     GLOAD(0, kt + 4);
.Lvm_down_ok:
	s_setprio 1
	ds_read_b128 v[168:171], v137
	ds_read_b128 v[208:211], v139 offset:36864
	ds_read_b128 v[212:215], v139 offset:38912
	ds_read_b128 v[220:223], v139 offset:40960
	ds_read_b128 v[224:227], v139 offset:43008
	ds_read_b128 v[228:231], v137 offset:2048
	ds_read_b128 v[232:235], v137 offset:4096
	ds_read_b128 v[236:239], v137 offset:6144
	s_waitcnt lgkmcnt(6)
	v_mfma_f32_16x16x32_bf16 v[124:127], v[208:211], v[168:171], v[124:127]
	ds_read_b128 v[240:243], v164
	ds_read_b128 v[244:247], v165 offset:36864
	s_waitcnt lgkmcnt(7)
	v_mfma_f32_16x16x32_bf16 v[120:123], v[212:215], v[168:171], v[120:123]
	s_waitcnt lgkmcnt(6)
	v_mfma_f32_16x16x32_bf16 v[116:119], v[220:223], v[168:171], v[116:119]
	s_waitcnt lgkmcnt(5)
	v_mfma_f32_16x16x32_bf16 v[112:115], v[224:227], v[168:171], v[112:115]
	ds_read_b128 v[168:171], v165 offset:38912
	s_waitcnt lgkmcnt(5)
	v_mfma_f32_16x16x32_bf16 v[108:111], v[208:211], v[228:231], v[108:111]
	v_mfma_f32_16x16x32_bf16 v[104:107], v[212:215], v[228:231], v[104:107]
	v_mfma_f32_16x16x32_bf16 v[100:103], v[220:223], v[228:231], v[100:103]
	v_mfma_f32_16x16x32_bf16 v[96:99], v[224:227], v[228:231], v[96:99]
	ds_read_b128 v[228:231], v165 offset:40960
	s_waitcnt lgkmcnt(5)
	v_mfma_f32_16x16x32_bf16 v[92:95], v[208:211], v[232:235], v[92:95]
	v_mfma_f32_16x16x32_bf16 v[88:91], v[212:215], v[232:235], v[88:91]
	v_mfma_f32_16x16x32_bf16 v[84:87], v[220:223], v[232:235], v[84:87]
	v_mfma_f32_16x16x32_bf16 v[80:83], v[224:227], v[232:235], v[80:83]
	ds_read_b128 v[232:235], v165 offset:43008
	s_waitcnt lgkmcnt(5)
	v_mfma_f32_16x16x32_bf16 v[76:79], v[208:211], v[236:239], v[76:79]
	ds_read_b128 v[208:211], v164 offset:2048
	v_mfma_f32_16x16x32_bf16 v[72:75], v[212:215], v[236:239], v[72:75]
	ds_read_b128 v[212:215], v164 offset:4096
	v_mfma_f32_16x16x32_bf16 v[68:71], v[220:223], v[236:239], v[68:71]
	ds_read_b128 v[220:223], v164 offset:6144
	v_mfma_f32_16x16x32_bf16 v[64:67], v[224:227], v[236:239], v[64:67]
	s_waitcnt vmcnt(8)
	v_cndmask_b32_e64 v0, 0, v0, s[2:3]
	v_cndmask_b32_e64 v1, 0, v1, s[2:3]
	v_cndmask_b32_e64 v2, 0, v2, s[2:3]
	v_cndmask_b32_e64 v3, 0, v3, s[2:3]
	ds_write_b128 v133, v[0:3] offset:18432
	s_waitcnt lgkmcnt(7)
	v_mfma_f32_16x16x32_bf16 v[124:127], v[244:247], v[240:243], v[124:127]
	s_waitcnt lgkmcnt(6)
	v_mfma_f32_16x16x32_bf16 v[120:123], v[168:171], v[240:243], v[120:123]
	v_cndmask_b32_e64 v4, 0, v4, s[4:5]
	v_cndmask_b32_e64 v5, 0, v5, s[4:5]
	v_cndmask_b32_e64 v6, 0, v6, s[4:5]
	v_cndmask_b32_e64 v7, 0, v7, s[4:5]
	ds_write_b128 v133, v[4:7] offset:22528
	s_waitcnt lgkmcnt(6)
	v_mfma_f32_16x16x32_bf16 v[116:119], v[228:231], v[240:243], v[116:119]
	s_waitcnt lgkmcnt(5)
	v_mfma_f32_16x16x32_bf16 v[112:115], v[232:235], v[240:243], v[112:115]
	v_cndmask_b32_e64 v8, 0, v8, s[6:7]
	v_cndmask_b32_e64 v9, 0, v9, s[6:7]
	v_cndmask_b32_e64 v10, 0, v10, s[6:7]
	v_cndmask_b32_e64 v11, 0, v11, s[6:7]
	ds_write_b128 v133, v[8:11] offset:26624
	s_waitcnt lgkmcnt(5)
	v_mfma_f32_16x16x32_bf16 v[108:111], v[244:247], v[208:211], v[108:111]
	v_mfma_f32_16x16x32_bf16 v[104:107], v[168:171], v[208:211], v[104:107]
	v_cndmask_b32_e64 v12, 0, v12, s[8:9]
	v_cndmask_b32_e64 v13, 0, v13, s[8:9]
	v_cndmask_b32_e64 v14, 0, v14, s[8:9]
	v_cndmask_b32_e64 v15, 0, v15, s[8:9]
	ds_write_b128 v133, v[12:15] offset:30720
	v_mfma_f32_16x16x32_bf16 v[100:103], v[228:231], v[208:211], v[100:103]
	v_mfma_f32_16x16x32_bf16 v[96:99], v[232:235], v[208:211], v[96:99]
	ds_write_b128 v133, v[16:19] offset:55296
	s_waitcnt lgkmcnt(6)
	v_mfma_f32_16x16x32_bf16 v[92:95], v[244:247], v[212:215], v[92:95]
	v_mfma_f32_16x16x32_bf16 v[88:91], v[168:171], v[212:215], v[88:91]
	ds_write_b128 v133, v[20:23] offset:59392
	v_mfma_f32_16x16x32_bf16 v[84:87], v[228:231], v[212:215], v[84:87]
	v_mfma_f32_16x16x32_bf16 v[80:83], v[232:235], v[212:215], v[80:83]
	ds_write_b128 v133, v[24:27] offset:63488
	s_waitcnt lgkmcnt(7)
	v_mfma_f32_16x16x32_bf16 v[76:79], v[244:247], v[220:223], v[76:79]
	v_mfma_f32_16x16x32_bf16 v[72:75], v[168:171], v[220:223], v[72:75]
	ds_write_b128 v135, v[32:35] offset:12288
	v_mfma_f32_16x16x32_bf16 v[68:71], v[228:231], v[220:223], v[68:71]
	v_mfma_f32_16x16x32_bf16 v[64:67], v[232:235], v[220:223], v[64:67]
	s_setprio 0
	s_cmp_gt_u32 s24, 40
	v_lshl_add_u64 v[162:163], v[144:145], 0, v[128:129]
	v_lshl_add_u64 v[160:161], v[146:147], 0, v[128:129]
	v_lshl_add_u64 v[158:159], v[148:149], 0, v[128:129]
	v_lshl_add_u64 v[156:157], v[150:151], 0, v[128:129]
	v_lshl_add_u64 v[154:155], v[152:153], 0, v[128:129]
	s_waitcnt lgkmcnt(0)
	s_barrier
	s_cbranch_scc1 .LBB0_876
	v_add_co_u32_e32 v20, vcc, 0x2c000, v154
	global_load_dwordx4 v[0:3], v[162:163], off offset:384
	global_load_dwordx4 v[4:7], v[160:161], off offset:384
	global_load_dwordx4 v[8:11], v[158:159], off offset:384
	global_load_dwordx4 v[12:15], v[156:157], off offset:384
	global_load_dwordx4 v[16:19], v[154:155], off offset:384
	v_addc_co_u32_e32 v21, vcc, 0, v155, vcc
	v_add_co_u32_e32 v24, vcc, 0x58000, v154
	s_nop 1
	v_addc_co_u32_e32 v25, vcc, 0, v155, vcc
	v_add_co_u32_e32 v32, vcc, 0x84000, v154
	global_load_dwordx4 v[20:23], v[20:21], off offset:384
	s_nop 0
	global_load_dwordx4 v[24:27], v[24:25], off offset:384
	v_addc_co_u32_e32 v33, vcc, 0, v155, vcc
	global_load_dwordx4 v[32:35], v[32:33], off offset:384
; template <bool ATRANS = false, bool SWAP = true>
; DEV void gemm_seg(f32x4 (&acc)[4][4], bf16_t* As, bf16_t* Bs, const bf16_t* A, const bf16_t* B, int lda, int ldb,
;                   int K, int arow_lo, int arow_hi) {
;     ...
;   GLOAD(0, 0);
;   GLOAD(1, 1);
;   STAB(0, 0);
;   GLOAD(0, 2);
;   for (int kt = 0; kt < nk; kt += 2) {
;     COMPUTE(kt);
;     STAB(1, kt + 1);
;     GLOAD(1, kt + 3);
;     if (kt + 1 >= nk) break;
;     COMPUTE(kt + 1);
;     STAB(0, kt + 2);
.LBB0_876:
	s_setprio 1
	ds_read_b128 v[168:171], v137 offset:18432
	ds_read_b128 v[208:211], v139 offset:55296
	ds_read_b128 v[212:215], v139 offset:57344
	ds_read_b128 v[220:223], v139 offset:59392
	ds_read_b128 v[224:227], v139 offset:61440
	ds_read_b128 v[228:231], v137 offset:20480
	ds_read_b128 v[232:235], v137 offset:22528
	ds_read_b128 v[236:239], v137 offset:24576
	s_waitcnt lgkmcnt(6)
	v_mfma_f32_16x16x32_bf16 v[124:127], v[208:211], v[168:171], v[124:127]
	ds_read_b128 v[240:243], v164 offset:18432
	ds_read_b128 v[244:247], v165 offset:55296
	s_waitcnt lgkmcnt(7)
	v_mfma_f32_16x16x32_bf16 v[120:123], v[212:215], v[168:171], v[120:123]
	s_waitcnt lgkmcnt(6)
	v_mfma_f32_16x16x32_bf16 v[116:119], v[220:223], v[168:171], v[116:119]
	s_waitcnt lgkmcnt(5)
	v_mfma_f32_16x16x32_bf16 v[112:115], v[224:227], v[168:171], v[112:115]
	ds_read_b128 v[168:171], v165 offset:57344
	s_waitcnt lgkmcnt(5)
	v_mfma_f32_16x16x32_bf16 v[108:111], v[208:211], v[228:231], v[108:111]
	v_mfma_f32_16x16x32_bf16 v[104:107], v[212:215], v[228:231], v[104:107]
	v_mfma_f32_16x16x32_bf16 v[100:103], v[220:223], v[228:231], v[100:103]
	v_mfma_f32_16x16x32_bf16 v[96:99], v[224:227], v[228:231], v[96:99]
	ds_read_b128 v[228:231], v165 offset:59392
	s_waitcnt lgkmcnt(5)
	v_mfma_f32_16x16x32_bf16 v[92:95], v[208:211], v[232:235], v[92:95]
	v_mfma_f32_16x16x32_bf16 v[88:91], v[212:215], v[232:235], v[88:91]
	v_mfma_f32_16x16x32_bf16 v[84:87], v[220:223], v[232:235], v[84:87]
	v_mfma_f32_16x16x32_bf16 v[80:83], v[224:227], v[232:235], v[80:83]
	ds_read_b128 v[232:235], v165 offset:61440
	s_waitcnt lgkmcnt(5)
	v_mfma_f32_16x16x32_bf16 v[76:79], v[208:211], v[236:239], v[76:79]
	ds_read_b128 v[208:211], v164 offset:20480
	v_mfma_f32_16x16x32_bf16 v[72:75], v[212:215], v[236:239], v[72:75]
	ds_read_b128 v[212:215], v164 offset:22528
	v_mfma_f32_16x16x32_bf16 v[68:71], v[220:223], v[236:239], v[68:71]
	ds_read_b128 v[220:223], v164 offset:24576
	v_mfma_f32_16x16x32_bf16 v[64:67], v[224:227], v[236:239], v[64:67]
	s_waitcnt vmcnt(8)
	v_cndmask_b32_e64 v28, 0, v28, s[2:3]
	v_cndmask_b32_e64 v29, 0, v29, s[2:3]
	v_cndmask_b32_e64 v30, 0, v30, s[2:3]
	v_cndmask_b32_e64 v31, 0, v31, s[2:3]
	ds_write_b128 v133, v[28:31]
	s_waitcnt lgkmcnt(7)
	v_mfma_f32_16x16x32_bf16 v[124:127], v[244:247], v[240:243], v[124:127]
	s_waitcnt lgkmcnt(6)
	v_mfma_f32_16x16x32_bf16 v[120:123], v[168:171], v[240:243], v[120:123]
	v_cndmask_b32_e64 v36, 0, v36, s[4:5]
	v_cndmask_b32_e64 v37, 0, v37, s[4:5]
	v_cndmask_b32_e64 v38, 0, v38, s[4:5]
	v_cndmask_b32_e64 v39, 0, v39, s[4:5]
	ds_write_b128 v133, v[36:39] offset:4096
	s_waitcnt lgkmcnt(6)
	v_mfma_f32_16x16x32_bf16 v[116:119], v[228:231], v[240:243], v[116:119]
	s_waitcnt lgkmcnt(5)
	v_mfma_f32_16x16x32_bf16 v[112:115], v[232:235], v[240:243], v[112:115]
	v_cndmask_b32_e64 v40, 0, v40, s[6:7]
	v_cndmask_b32_e64 v41, 0, v41, s[6:7]
	v_cndmask_b32_e64 v42, 0, v42, s[6:7]
	v_cndmask_b32_e64 v43, 0, v43, s[6:7]
	ds_write_b128 v133, v[40:43] offset:8192
	s_waitcnt lgkmcnt(5)
	v_mfma_f32_16x16x32_bf16 v[108:111], v[244:247], v[208:211], v[108:111]
	v_mfma_f32_16x16x32_bf16 v[104:107], v[168:171], v[208:211], v[104:107]
	v_cndmask_b32_e64 v44, 0, v44, s[8:9]
	v_cndmask_b32_e64 v45, 0, v45, s[8:9]
	v_cndmask_b32_e64 v46, 0, v46, s[8:9]
	v_cndmask_b32_e64 v47, 0, v47, s[8:9]
	ds_write_b128 v133, v[44:47] offset:12288
	v_mfma_f32_16x16x32_bf16 v[100:103], v[228:231], v[208:211], v[100:103]
	v_mfma_f32_16x16x32_bf16 v[96:99], v[232:235], v[208:211], v[96:99]
	ds_write_b128 v133, v[48:51] offset:36864
	s_waitcnt lgkmcnt(6)
	v_mfma_f32_16x16x32_bf16 v[92:95], v[244:247], v[212:215], v[92:95]
	v_mfma_f32_16x16x32_bf16 v[88:91], v[168:171], v[212:215], v[88:91]
	ds_write_b128 v133, v[52:55] offset:40960
	v_mfma_f32_16x16x32_bf16 v[84:87], v[228:231], v[212:215], v[84:87]
	v_mfma_f32_16x16x32_bf16 v[80:83], v[232:235], v[212:215], v[80:83]
	ds_write_b128 v133, v[56:59] offset:45056
	s_waitcnt lgkmcnt(7)
	v_mfma_f32_16x16x32_bf16 v[76:79], v[244:247], v[220:223], v[76:79]
	v_mfma_f32_16x16x32_bf16 v[72:75], v[168:171], v[220:223], v[72:75]
	ds_write_b128 v133, v[60:63] offset:49152
	v_mfma_f32_16x16x32_bf16 v[68:71], v[228:231], v[220:223], v[68:71]
	v_mfma_f32_16x16x32_bf16 v[64:67], v[232:235], v[220:223], v[64:67]
	s_setprio 0
	s_cmp_gt_u32 s24, 41
	s_cselect_b64 s[0:1], -1, 0

; template <bool ATRANS = false, bool SWAP = true>
; DEV void gemm_seg(f32x4 (&acc)[4][4], bf16_t* As, bf16_t* Bs, const bf16_t* A, const bf16_t* B, int lda, int ldb,
;                   int K, int arow_lo, int arow_hi) {
;     ...
;   GLOAD(0, 0);
;   GLOAD(1, 1);
;   STAB(0, 0);
;   GLOAD(0, 2);
;   for (int kt = 0; kt < nk; kt += 2) {
;     COMPUTE(kt);
;     STAB(1, kt + 1);
;     GLOAD(1, kt + 3);
;     if (kt + 1 >= nk) break;
;     COMPUTE(kt + 1);
;     STAB(0, kt + 2);
;     GLOAD(0, kt + 4);
.Lvm_pleg_ok:
	s_setprio 1
	ds_read_b128 v[168:171], v137
	ds_read_b128 v[208:211], v139 offset:36864
	ds_read_b128 v[212:215], v139 offset:38912
	ds_read_b128 v[220:223], v139 offset:40960
	ds_read_b128 v[224:227], v139 offset:43008
	ds_read_b128 v[228:231], v137 offset:2048
	ds_read_b128 v[232:235], v137 offset:4096
	ds_read_b128 v[236:239], v137 offset:6144
	s_waitcnt lgkmcnt(6)
	v_mfma_f32_16x16x32_bf16 v[124:127], v[208:211], v[168:171], v[124:127]
	ds_read_b128 v[240:243], v164
	ds_read_b128 v[244:247], v165 offset:36864
	s_waitcnt lgkmcnt(7)
	v_mfma_f32_16x16x32_bf16 v[120:123], v[212:215], v[168:171], v[120:123]
	s_waitcnt lgkmcnt(6)
	v_mfma_f32_16x16x32_bf16 v[116:119], v[220:223], v[168:171], v[116:119]
	s_waitcnt lgkmcnt(5)
	v_mfma_f32_16x16x32_bf16 v[112:115], v[224:227], v[168:171], v[112:115]
	ds_read_b128 v[168:171], v165 offset:38912
	s_waitcnt lgkmcnt(5)
	v_mfma_f32_16x16x32_bf16 v[108:111], v[208:211], v[228:231], v[108:111]
	v_mfma_f32_16x16x32_bf16 v[104:107], v[212:215], v[228:231], v[104:107]
	v_mfma_f32_16x16x32_bf16 v[100:103], v[220:223], v[228:231], v[100:103]
	v_mfma_f32_16x16x32_bf16 v[96:99], v[224:227], v[228:231], v[96:99]
	ds_read_b128 v[228:231], v165 offset:40960
	s_waitcnt lgkmcnt(5)
	v_mfma_f32_16x16x32_bf16 v[92:95], v[208:211], v[232:235], v[92:95]
	v_mfma_f32_16x16x32_bf16 v[88:91], v[212:215], v[232:235], v[88:91]
	v_mfma_f32_16x16x32_bf16 v[84:87], v[220:223], v[232:235], v[84:87]
	v_mfma_f32_16x16x32_bf16 v[80:83], v[224:227], v[232:235], v[80:83]
	ds_read_b128 v[232:235], v165 offset:43008
	s_waitcnt lgkmcnt(5)
	v_mfma_f32_16x16x32_bf16 v[76:79], v[208:211], v[236:239], v[76:79]
	ds_read_b128 v[208:211], v164 offset:2048
	v_mfma_f32_16x16x32_bf16 v[72:75], v[212:215], v[236:239], v[72:75]
	ds_read_b128 v[212:215], v164 offset:4096
	v_mfma_f32_16x16x32_bf16 v[68:71], v[220:223], v[236:239], v[68:71]
	ds_read_b128 v[220:223], v164 offset:6144
	v_mfma_f32_16x16x32_bf16 v[64:67], v[224:227], v[236:239], v[64:67]
	s_waitcnt vmcnt(8)
	v_cndmask_b32_e64 v0, 0, v0, s[2:3]
	v_cndmask_b32_e64 v1, 0, v1, s[2:3]
	v_cndmask_b32_e64 v2, 0, v2, s[2:3]
	v_cndmask_b32_e64 v3, 0, v3, s[2:3]
	ds_write_b128 v133, v[0:3] offset:18432
	s_waitcnt lgkmcnt(7)
	v_mfma_f32_16x16x32_bf16 v[124:127], v[244:247], v[240:243], v[124:127]
	s_waitcnt lgkmcnt(6)
	v_mfma_f32_16x16x32_bf16 v[120:123], v[168:171], v[240:243], v[120:123]
	v_cndmask_b32_e64 v4, 0, v4, s[4:5]
	v_cndmask_b32_e64 v5, 0, v5, s[4:5]
	v_cndmask_b32_e64 v6, 0, v6, s[4:5]
	v_cndmask_b32_e64 v7, 0, v7, s[4:5]
	ds_write_b128 v133, v[4:7] offset:22528
	s_waitcnt lgkmcnt(6)
	v_mfma_f32_16x16x32_bf16 v[116:119], v[228:231], v[240:243], v[116:119]
	s_waitcnt lgkmcnt(5)
	v_mfma_f32_16x16x32_bf16 v[112:115], v[232:235], v[240:243], v[112:115]
	v_cndmask_b32_e64 v8, 0, v8, s[6:7]
	v_cndmask_b32_e64 v9, 0, v9, s[6:7]
	v_cndmask_b32_e64 v10, 0, v10, s[6:7]
	v_cndmask_b32_e64 v11, 0, v11, s[6:7]
	ds_write_b128 v133, v[8:11] offset:26624
	s_waitcnt lgkmcnt(5)
	v_mfma_f32_16x16x32_bf16 v[108:111], v[244:247], v[208:211], v[108:111]
	v_mfma_f32_16x16x32_bf16 v[104:107], v[168:171], v[208:211], v[104:107]
	v_cndmask_b32_e64 v12, 0, v12, s[8:9]
	v_cndmask_b32_e64 v13, 0, v13, s[8:9]
	v_cndmask_b32_e64 v14, 0, v14, s[8:9]
	v_cndmask_b32_e64 v15, 0, v15, s[8:9]
	ds_write_b128 v133, v[12:15] offset:30720
	v_mfma_f32_16x16x32_bf16 v[100:103], v[228:231], v[208:211], v[100:103]
	v_mfma_f32_16x16x32_bf16 v[96:99], v[232:235], v[208:211], v[96:99]
	ds_write_b128 v133, v[16:19] offset:55296
	s_waitcnt lgkmcnt(6)
	v_mfma_f32_16x16x32_bf16 v[92:95], v[244:247], v[212:215], v[92:95]
	v_mfma_f32_16x16x32_bf16 v[88:91], v[168:171], v[212:215], v[88:91]
	ds_write_b128 v133, v[20:23] offset:59392
	v_mfma_f32_16x16x32_bf16 v[84:87], v[228:231], v[212:215], v[84:87]
	v_mfma_f32_16x16x32_bf16 v[80:83], v[232:235], v[212:215], v[80:83]
	ds_write_b128 v133, v[24:27] offset:63488
	s_waitcnt lgkmcnt(7)
	v_mfma_f32_16x16x32_bf16 v[76:79], v[244:247], v[220:223], v[76:79]
	v_mfma_f32_16x16x32_bf16 v[72:75], v[168:171], v[220:223], v[72:75]
	ds_write_b128 v135, v[32:35] offset:12288
	v_mfma_f32_16x16x32_bf16 v[68:71], v[228:231], v[220:223], v[68:71]
	v_mfma_f32_16x16x32_bf16 v[64:67], v[232:235], v[220:223], v[64:67]
	s_setprio 0
	s_cmp_gt_u32 s22, 12
	v_lshl_add_u64 v[162:163], v[144:145], 0, v[128:129]
	v_lshl_add_u64 v[160:161], v[146:147], 0, v[128:129]
	v_lshl_add_u64 v[158:159], v[148:149], 0, v[128:129]
	v_lshl_add_u64 v[156:157], v[150:151], 0, v[128:129]
	v_lshl_add_u64 v[154:155], v[152:153], 0, v[128:129]
	s_waitcnt lgkmcnt(0)
	s_barrier
	s_cbranch_scc1 .LBB0_926
	v_add_co_u32_e32 v20, vcc, 0x10000, v154
	global_load_dwordx4 v[0:3], v[162:163], off offset:384
	global_load_dwordx4 v[4:7], v[160:161], off offset:384
	global_load_dwordx4 v[8:11], v[158:159], off offset:384
	global_load_dwordx4 v[12:15], v[156:157], off offset:384
	global_load_dwordx4 v[16:19], v[154:155], off offset:384
	v_addc_co_u32_e32 v21, vcc, 0, v155, vcc
	v_add_co_u32_e32 v24, vcc, 0x20000, v154
	s_nop 1
	v_addc_co_u32_e32 v25, vcc, 0, v155, vcc
	v_add_co_u32_e32 v32, vcc, 0x30000, v154
	global_load_dwordx4 v[20:23], v[20:21], off offset:384
	s_nop 0
	global_load_dwordx4 v[24:27], v[24:25], off offset:384
	v_addc_co_u32_e32 v33, vcc, 0, v155, vcc
	global_load_dwordx4 v[32:35], v[32:33], off offset:384
; template <bool ATRANS = false, bool SWAP = true>
; DEV void gemm_seg(f32x4 (&acc)[4][4], bf16_t* As, bf16_t* Bs, const bf16_t* A, const bf16_t* B, int lda, int ldb,
;                   int K, int arow_lo, int arow_hi) {
;     ...
;   GLOAD(0, 0);
;   GLOAD(1, 1);
;   STAB(0, 0);
;   GLOAD(0, 2);
;   for (int kt = 0; kt < nk; kt += 2) {
;     COMPUTE(kt);
;     STAB(1, kt + 1);
;     GLOAD(1, kt + 3);
;     if (kt + 1 >= nk) break;
;     COMPUTE(kt + 1);
;     STAB(0, kt + 2);
.LBB0_926:
	s_setprio 1
	ds_read_b128 v[168:171], v137 offset:18432
	ds_read_b128 v[208:211], v139 offset:55296
	ds_read_b128 v[212:215], v139 offset:57344
	ds_read_b128 v[220:223], v139 offset:59392
	ds_read_b128 v[224:227], v139 offset:61440
	ds_read_b128 v[228:231], v137 offset:20480
	ds_read_b128 v[232:235], v137 offset:22528
	ds_read_b128 v[236:239], v137 offset:24576
	s_waitcnt lgkmcnt(6)
	v_mfma_f32_16x16x32_bf16 v[124:127], v[208:211], v[168:171], v[124:127]
	ds_read_b128 v[240:243], v164 offset:18432
	ds_read_b128 v[244:247], v165 offset:55296
	s_waitcnt lgkmcnt(7)
	v_mfma_f32_16x16x32_bf16 v[120:123], v[212:215], v[168:171], v[120:123]
	s_waitcnt lgkmcnt(6)
	v_mfma_f32_16x16x32_bf16 v[116:119], v[220:223], v[168:171], v[116:119]
	s_waitcnt lgkmcnt(5)
	v_mfma_f32_16x16x32_bf16 v[112:115], v[224:227], v[168:171], v[112:115]
	ds_read_b128 v[168:171], v165 offset:57344
	s_waitcnt lgkmcnt(5)
	v_mfma_f32_16x16x32_bf16 v[108:111], v[208:211], v[228:231], v[108:111]
	v_mfma_f32_16x16x32_bf16 v[104:107], v[212:215], v[228:231], v[104:107]
	v_mfma_f32_16x16x32_bf16 v[100:103], v[220:223], v[228:231], v[100:103]
	v_mfma_f32_16x16x32_bf16 v[96:99], v[224:227], v[228:231], v[96:99]
	ds_read_b128 v[228:231], v165 offset:59392
	s_waitcnt lgkmcnt(5)
	v_mfma_f32_16x16x32_bf16 v[92:95], v[208:211], v[232:235], v[92:95]
	v_mfma_f32_16x16x32_bf16 v[88:91], v[212:215], v[232:235], v[88:91]
	v_mfma_f32_16x16x32_bf16 v[84:87], v[220:223], v[232:235], v[84:87]
	v_mfma_f32_16x16x32_bf16 v[80:83], v[224:227], v[232:235], v[80:83]
	ds_read_b128 v[232:235], v165 offset:61440
	s_waitcnt lgkmcnt(5)
	v_mfma_f32_16x16x32_bf16 v[76:79], v[208:211], v[236:239], v[76:79]
	ds_read_b128 v[208:211], v164 offset:20480
	v_mfma_f32_16x16x32_bf16 v[72:75], v[212:215], v[236:239], v[72:75]
	ds_read_b128 v[212:215], v164 offset:22528
	v_mfma_f32_16x16x32_bf16 v[68:71], v[220:223], v[236:239], v[68:71]
	ds_read_b128 v[220:223], v164 offset:24576
	v_mfma_f32_16x16x32_bf16 v[64:67], v[224:227], v[236:239], v[64:67]
	s_waitcnt vmcnt(8)
	v_cndmask_b32_e64 v28, 0, v28, s[2:3]
	v_cndmask_b32_e64 v29, 0, v29, s[2:3]
	v_cndmask_b32_e64 v30, 0, v30, s[2:3]
	v_cndmask_b32_e64 v31, 0, v31, s[2:3]
	ds_write_b128 v133, v[28:31]
	s_waitcnt lgkmcnt(7)
	v_mfma_f32_16x16x32_bf16 v[124:127], v[244:247], v[240:243], v[124:127]
	s_waitcnt lgkmcnt(6)
	v_mfma_f32_16x16x32_bf16 v[120:123], v[168:171], v[240:243], v[120:123]
	v_cndmask_b32_e64 v36, 0, v36, s[4:5]
	v_cndmask_b32_e64 v37, 0, v37, s[4:5]
	v_cndmask_b32_e64 v38, 0, v38, s[4:5]
	v_cndmask_b32_e64 v39, 0, v39, s[4:5]
	ds_write_b128 v133, v[36:39] offset:4096
	s_waitcnt lgkmcnt(6)
	v_mfma_f32_16x16x32_bf16 v[116:119], v[228:231], v[240:243], v[116:119]
	s_waitcnt lgkmcnt(5)
	v_mfma_f32_16x16x32_bf16 v[112:115], v[232:235], v[240:243], v[112:115]
	v_cndmask_b32_e64 v40, 0, v40, s[6:7]
	v_cndmask_b32_e64 v41, 0, v41, s[6:7]
	v_cndmask_b32_e64 v42, 0, v42, s[6:7]
	v_cndmask_b32_e64 v43, 0, v43, s[6:7]
	ds_write_b128 v133, v[40:43] offset:8192
	s_waitcnt lgkmcnt(5)
	v_mfma_f32_16x16x32_bf16 v[108:111], v[244:247], v[208:211], v[108:111]
	v_mfma_f32_16x16x32_bf16 v[104:107], v[168:171], v[208:211], v[104:107]
	v_cndmask_b32_e64 v44, 0, v44, s[8:9]
	v_cndmask_b32_e64 v45, 0, v45, s[8:9]
	v_cndmask_b32_e64 v46, 0, v46, s[8:9]
	v_cndmask_b32_e64 v47, 0, v47, s[8:9]
	ds_write_b128 v133, v[44:47] offset:12288
	v_mfma_f32_16x16x32_bf16 v[100:103], v[228:231], v[208:211], v[100:103]
	v_mfma_f32_16x16x32_bf16 v[96:99], v[232:235], v[208:211], v[96:99]
	ds_write_b128 v133, v[48:51] offset:36864
	s_waitcnt lgkmcnt(6)
	v_mfma_f32_16x16x32_bf16 v[92:95], v[244:247], v[212:215], v[92:95]
	v_mfma_f32_16x16x32_bf16 v[88:91], v[168:171], v[212:215], v[88:91]
	ds_write_b128 v133, v[52:55] offset:40960
	v_mfma_f32_16x16x32_bf16 v[84:87], v[228:231], v[212:215], v[84:87]
	v_mfma_f32_16x16x32_bf16 v[80:83], v[232:235], v[212:215], v[80:83]
	ds_write_b128 v133, v[56:59] offset:45056
	s_waitcnt lgkmcnt(7)
	v_mfma_f32_16x16x32_bf16 v[76:79], v[244:247], v[220:223], v[76:79]
	v_mfma_f32_16x16x32_bf16 v[72:75], v[168:171], v[220:223], v[72:75]
	ds_write_b128 v133, v[60:63] offset:49152
	v_mfma_f32_16x16x32_bf16 v[68:71], v[228:231], v[220:223], v[68:71]
	v_mfma_f32_16x16x32_bf16 v[64:67], v[232:235], v[220:223], v[64:67]
	s_setprio 0
	s_cmp_gt_u32 s22, 13
	s_cselect_b64 s[0:1], -1, 0
